# v012 + attention finalize: head-norm gain loads issued together (no per-chunk load/wait/store chain)
# speedup vs baseline: 1.0152x; 1.0033x over previous
; DI unsigned pk2(float lo, float hi) { const f32x2 v = {lo, hi}; return __builtin_bit_cast(unsigned, __builtin_convertvector(v, hwbf16x2)); }
; template <int VAR>
; DI void attn_segment(const Args& a, const Frame& F, int l, int qrow0, int qpos0, int hp, int ntile, int nf32, const float* ck, const float* cv, int prow0) {
;     ...
;     float l1 = S.l1, l2 = S.l2;
;     l1 += __shfl_xor(l1, 16); l1 += __shfl_xor(l1, 32); l2 += __shfl_xor(l2, 16); l2 += __shfl_xor(l2, 32);
;     const float lam = ((const float*)(sm + S_LAM))[0], lam_init = ((const float*)(sm + S_LAM))[1];
;     const float i1 = 1.f / l1, i2 = lam / l2;
;     float ss = 0.f;
; #pragma unroll
;     for (int dt = 0; dt < 4; ++dt)
; #pragma unroll
;         for (int j = 0; j < 4; ++j) { const float o = S.O1[dt][j] * i1 - S.O2[dt][j] * i2; S.O1[dt][j] = o; ss += o * o; }
;     ss += __shfl_xor(ss, 16); ss += __shfl_xor(ss, 32);
;     const float rs = (1.f - lam_init) / sqrtf(ss * (1.f / 64.f) + EPS);
;     bf16* op = MIX + (size_t)(qrow0 + qr + fr) * DM + 256 + h * 64 + 4 * fq;
; #pragma unroll
;     for (int dt = 0; dt < 4; ++dt) { const f32x4 gn = *(const f32x4*)(a.in[I_DNORM] + l * 64 + 16 * dt + 4 * fq);
;         u32x2 w; w.x = pk2(S.O1[dt][0] * rs * gn[0], S.O1[dt][1] * rs * gn[1]); w.y = pk2(S.O1[dt][2] * rs * gn[2], S.O1[dt][3] * rs * gn[3]);
;         *(u32x2*)(op + 16 * dt) = w; }
.LBB0_1418:
	global_load_dword v28, v2, s[12:13]
	v_ashrrev_i32_e32 v143, 31, v142
	v_lshl_add_u64 v[26:27], v[142:143], 2, s[10:11]
	global_load_dwordx4 v[22:25], v[26:27], off
	global_load_dwordx4 v[230:233], v[26:27], off offset:64
	global_load_dwordx4 v[234:237], v[26:27], off offset:128
	global_load_dwordx4 v[238:241], v[26:27], off offset:192
	s_waitcnt lgkmcnt(0)
	v_add_f32_e32 v3, v3, v20
	v_fmamk_f32 v3, v3, 0x3c800000, v1
	v_mul_f32_e32 v29, 0x4f800000, v3
	v_cmp_gt_f32_e32 vcc, s67, v3
	v_lshlrev_b64 v[20:21], 11, v[140:141]
	v_lshl_add_u64 v[20:21], s[74:75], 0, v[20:21]
	v_cndmask_b32_e32 v3, v3, v29, vcc
	v_sqrt_f32_e32 v29, v3
	v_lshl_add_u64 v[20:21], s[2:3], 1, v[20:21]
	v_lshl_add_u64 v[20:21], v[142:143], 1, v[20:21]
	v_add_u32_e32 v30, -1, v29
	v_add_u32_e32 v31, 1, v29
	v_fma_f32 v32, -v30, v29, v3
	v_fma_f32 v33, -v31, v29, v3
	v_cmp_ge_f32_e64 s[2:3], 0, v32
	s_nop 1
	v_cndmask_b32_e64 v29, v29, v30, s[2:3]
	v_cmp_lt_f32_e64 s[2:3], 0, v33
	s_nop 1
	v_cndmask_b32_e64 v29, v29, v31, s[2:3]
	v_mul_f32_e32 v30, 0x37800000, v29
	v_cndmask_b32_e32 v29, v29, v30, vcc
	v_cmp_class_f32_e32 vcc, v3, v196
	s_waitcnt vmcnt(0)
	v_sub_f32_e32 v30, 1.0, v28
	v_cndmask_b32_e32 v3, v29, v3, vcc
	v_div_scale_f32 v31, s[0:1], v3, v3, v30
	v_rcp_f32_e32 v32, v31
	s_mov_b32 s0, 0x1b300000
	v_add_co_u32_e32 v28, vcc, s0, v20
	v_fma_f32 v34, -v31, v32, 1.0
	s_nop 0
	v_addc_co_u32_e32 v29, vcc, 0, v21, vcc
	v_div_scale_f32 v33, vcc, v30, v3, v30
	v_fmac_f32_e32 v32, v34, v32
	v_mul_f32_e32 v34, v33, v32
	v_fma_f32 v35, -v31, v34, v33
	v_fmac_f32_e32 v34, v35, v32
	v_fma_f32 v31, -v31, v34, v33
	v_div_fmas_f32 v31, v31, v32, v34
	v_div_fixup_f32 v30, v31, v3, v30
	v_pk_mul_f32 v[18:19], v[18:19], v[30:31] op_sel_hi:[1,0]
	v_pk_mul_f32 v[16:17], v[16:17], v[30:31] op_sel_hi:[1,0]
	v_pk_mul_f32 v[18:19], v[22:23], v[18:19]
	v_pk_mul_f32 v[16:17], v[24:25], v[16:17]
	v_cvt_pk_bf16_f32 v18, v18, v19
	v_cvt_pk_bf16_f32 v19, v16, v17
	global_store_dwordx2 v[28:29], v[18:19], off offset:512
	v_pk_mul_f32 v[14:15], v[14:15], v[30:31] op_sel_hi:[1,0]
	v_pk_mul_f32 v[12:13], v[12:13], v[30:31] op_sel_hi:[1,0]
	s_mov_b64 s[0:1], 0x1b300200
	v_lshl_add_u64 v[20:21], v[20:21], 0, s[0:1]
	v_pk_mul_f32 v[10:11], v[10:11], v[30:31] op_sel_hi:[1,0]
	v_pk_mul_f32 v[8:9], v[8:9], v[30:31] op_sel_hi:[1,0]
	v_pk_mul_f32 v[6:7], v[6:7], v[30:31] op_sel_hi:[1,0]
	v_pk_mul_f32 v[4:5], v[4:5], v[30:31] op_sel_hi:[1,0]
	v_pk_mul_f32 v[14:15], v[14:15], v[230:231]
	v_pk_mul_f32 v[12:13], v[12:13], v[232:233]
	v_cvt_pk_bf16_f32 v14, v14, v15
	v_cvt_pk_bf16_f32 v15, v12, v13
	global_store_dwordx2 v[20:21], v[14:15], off offset:32
	v_pk_mul_f32 v[10:11], v[10:11], v[234:235]
	v_pk_mul_f32 v[8:9], v[8:9], v[236:237]
	v_cvt_pk_bf16_f32 v10, v10, v11
	v_cvt_pk_bf16_f32 v11, v8, v9
	global_store_dwordx2 v[20:21], v[10:11], off offset:64
	v_pk_mul_f32 v[6:7], v[6:7], v[238:239]
	v_pk_mul_f32 v[4:5], v[4:5], v[240:241]
	v_cvt_pk_bf16_f32 v6, v6, v7
	v_cvt_pk_bf16_f32 v7, v4, v5
	global_store_dwordx2 v[20:21], v[6:7], off offset:96
	s_barrier
	s_and_saveexec_b64 s[0:1], s[36:37]
	s_cbranch_execz .LBB0_1368
	v_mov_b32_e32 v3, s79
	ds_write_b32 v3, v161
	s_branch .LBB0_1368
